# MoBA phase: static s_setprio 1 for waves 4-7 (second wave of every SIMD), reset at phase end; on top of v050
# baseline (speedup 1.0000x reference)
.LBB0_87:
	s_or_b64 exec, exec, s[4:5]
	v_readlane_b32 s0, v252, 9
	v_readlane_b32 s1, v252, 10
	s_waitcnt vmcnt(2)
	v_mov_b32_e32 v4, v173
	s_andn2_b64 vcc, exec, s[0:1]
	s_barrier
	s_cbranch_vccnz .LBB0_159
	v_readfirstlane_b32 s0, v4
	s_lshr_b32 s0, s0, 8
	s_cmp_eq_u32 s0, 0
	s_cbranch_scc1 .Lmoba_noprio
	s_setprio 1
.Lmoba_noprio:
	v_ashrrev_i32_e32 v1, 2, v4
	v_readlane_b32 s0, v253, 37
	v_bfi_b32 v157, -16, v1, v4
	s_waitcnt lgkmcnt(0)
	v_and_b32_e32 v5, 15, v4
	v_and_b32_e32 v6, -16, v1
	v_and_b32_e32 v8, 0x7f, v4
	v_mov_b32_e32 v10, s0
	s_movk_i32 s1, 0x84
	s_movk_i32 s0, 0x80
	v_mul_lo_u32 v1, v157, s64
	v_mul_u32_u24_e32 v135, 0x110, v8
	v_mad_u32_u24 v8, v8, s1, v10
	v_cmp_gt_i32_e64 s[4:5], s0, v4
	v_add_u32_e32 v10, 0, v1
	v_lshlrev_b32_e32 v1, 2, v6
	v_lshlrev_b32_e32 v6, 2, v5
	v_readlane_b32 s0, v253, 38
	v_and_b32_e32 v7, 63, v4
	v_lshlrev_b32_e32 v0, 4, v5
	v_add3_u32 v159, s0, v1, v6
	v_and_b32_e32 v6, 64, v214
	v_xor_b32_e32 v1, 1, v214
	v_add_u32_e32 v6, 64, v6
	v_cmp_lt_i32_e32 vcc, v1, v6
	v_lshl_add_u32 v164, v7, 2, s0
	v_and_b32_e32 v7, 3, v4
	v_cndmask_b32_e32 v1, v214, v1, vcc
	v_lshlrev_b32_e32 v160, 2, v1
	v_xor_b32_e32 v1, 2, v214
	v_cmp_lt_i32_e32 vcc, v1, v6
	v_lshlrev_b32_e32 v11, 5, v7
	v_subrev_u32_e32 v12, 56, v11
	v_cndmask_b32_e32 v1, v214, v1, vcc
	v_lshlrev_b32_e32 v161, 2, v1
	v_xor_b32_e32 v1, 4, v214
	v_cmp_lt_i32_e32 vcc, v1, v6
	v_readlane_b32 s6, v254, 48
	v_readlane_b32 s7, v254, 49
	v_cndmask_b32_e32 v1, v214, v1, vcc
	v_lshlrev_b32_e32 v162, 2, v1
	v_xor_b32_e32 v1, 8, v214
	v_cmp_lt_i32_e32 vcc, v1, v6
	v_lshlrev_b32_e32 v2, 3, v5
	v_mul_u32_u24_e32 v167, 0x220, v5
	v_cndmask_b32_e32 v1, v214, v1, vcc
	v_cmp_gt_u32_e32 vcc, 2, v7
	v_lshlrev_b32_e32 v163, 2, v1
	v_and_b32_e32 v1, 0xc0, v0
	v_cndmask_b32_e32 v7, v12, v11, vcc
	v_add_u32_e32 v165, v7, v1
	v_mov_b32_e32 v1, v3
	v_lshl_add_u64 v[118:119], s[6:7], 0, v[0:1]
	v_lshrrev_b32_e32 v1, 2, v4
	v_and_b32_e32 v120, 12, v1
	v_xor_b32_e32 v1, 16, v214
	v_cmp_lt_i32_e32 vcc, v1, v6
	v_add_u32_e32 v5, 0x400, v4
	v_ashrrev_i32_e32 v124, 4, v5
	v_cndmask_b32_e32 v1, v214, v1, vcc
	v_lshlrev_b32_e32 v168, 2, v1
	v_xor_b32_e32 v1, 32, v214
	v_cmp_lt_i32_e32 vcc, v1, v6
	v_add_u32_e32 v5, 0x600, v4
	v_ashrrev_i32_e32 v9, 7, v4
	v_cndmask_b32_e32 v1, v214, v1, vcc
	v_lshl_add_u32 v166, v4, 2, s0
	v_lshlrev_b32_e32 v169, 2, v1
	v_add_u32_e32 v1, 0x200, v4
	v_ashrrev_i32_e32 v126, 4, v5
	v_ashrrev_i32_e32 v5, 31, v4
	v_readlane_b32 s0, v253, 36
	v_and_b32_e32 v158, 48, v4
	v_ashrrev_i32_e32 v116, 4, v4
	v_mul_lo_u32 v7, v4, s1
	v_ashrrev_i32_e32 v122, 4, v1
	v_lshl_add_u32 v171, v4, 4, s0
	v_lshl_add_u32 v175, v1, 4, s0
	v_lshlrev_b32_e32 v1, 3, v9
	v_lshl_add_u64 v[4:5], v[4:5], 4, s[6:7]
	s_mov_b64 s[0:1], 0x13ec0400
	v_add_u32_e32 v133, 0, v0
	v_add_u32_e32 v11, 0, v165
	v_mul_lo_u32 v170, v116, s64
	v_and_b32_e32 v216, 15, v116
	v_lshrrev_b32_e32 v217, 4, v116
	v_lshl_add_u32 v216, v216, 1, v217
	v_mul_u32_u24_e32 v216, 0x110, v216
	v_add_u32_e32 v217, v133, v216
	v_mul_lo_u32 v6, v122, s64
	v_mul_lo_u32 v12, v124, s64
	v_mul_lo_u32 v13, v126, s64
	v_or_b32_e32 v130, 2, v1
	v_or_b32_e32 v132, 4, v1
	v_or_b32_e32 v134, 6, v1
	v_lshl_add_u64 v[136:137], v[4:5], 0, s[0:1]
	v_add_u32_e32 v4, 0, v7
	v_lshlrev_b32_e32 v156, 12, v9
	v_ashrrev_i32_e32 v117, 31, v116
	v_ashrrev_i32_e32 v123, 31, v122
	v_ashrrev_i32_e32 v125, 31, v124
	v_ashrrev_i32_e32 v127, 31, v126
	v_lshl_add_u32 v184, v9, 5, v8
	v_or_b32_e32 v128, 1, v1
	v_or_b32_e32 v121, 3, v1
	v_lshl_add_u32 v185, v130, 2, v8
	v_or_b32_e32 v129, 5, v1
	v_lshl_add_u32 v186, v132, 2, v8
	v_or_b32_e32 v131, 7, v1
	v_lshl_add_u32 v187, v134, 2, v8
	v_lshlrev_b32_e32 v2, 1, v2
	v_add_u32_e32 v188, v133, v6
	v_add_u32_e32 v189, v133, v12
	v_add_u32_e32 v190, v133, v13
	v_add_u32_e32 v191, 0x15000, v4
	v_add_u32_e32 v192, v10, v158
	v_add_u32_e32 v193, v11, v216
	v_lshlrev_b32_e32 v138, 1, v120
	s_mov_b32 s42, s66
	s_branch .LBB0_90

.LBB0_159:
	s_setprio 0
	s_mov_b64 s[0:1], 0
